# nt hint also on the norm0 first-row prologue x loads (every x read in norm0 is now streaming)
# baseline (speedup 1.0000x reference)
.LBB0_661:
	s_getreg_b32 s0, hwreg(HW_REG_HW_ID, 0, 6)
	s_lshl_b32 s0, s0, 2
	s_and_b32 s0, s0, 0xfc
	s_add_i32 s1, 0, 0x256c0
	s_add_i32 s0, s1, s0
	v_mov_b32_e32 v0, s0
	ds_read_b32 v0, v0
	v_mbcnt_lo_u32_b32 v1, -1, 0
	v_mbcnt_hi_u32_b32 v1, -1, v1
	s_getreg_b32 s0, hwreg(HW_REG_HW_ID, 0, 6)
	s_lshl_b32 s0, s0, 2
	s_and_b32 s0, s0, 0xfc
	s_waitcnt lgkmcnt(0)
	v_readfirstlane_b32 s3, v0
	s_add_i32 s0, s1, s0
	s_nop 0
	v_lshl_add_u32 v0, s3, 6, v1
	v_mov_b32_e32 v1, s0
	ds_read_b32 v1, v1
	v_ashrrev_i32_e32 v0, 6, v0
	v_lshl_add_u32 v28, s2, 3, v0
	s_mov_b32 s3, 0x8800
	v_cmp_gt_i32_e32 vcc, s3, v28
	v_mbcnt_lo_u32_b32 v20, -1, 0
	v_mbcnt_hi_u32_b32 v20, -1, v20
	s_and_saveexec_b64 s[0:1], vcc
	s_cbranch_execz .LBB0_664
	s_mov_b32 s14, 0x8000
	v_add_u32_e32 v0, 0xffff8000, v28
	v_ashrrev_i32_e32 v29, 31, v28
	v_cmp_gt_i32_e32 vcc, s14, v28
	v_mov_b32_e32 v2, s57
	v_mov_b32_e32 v3, s53
	s_waitcnt lgkmcnt(0)
	v_cndmask_b32_e32 v1, 0, v29, vcc
	v_cndmask_b32_e32 v0, v0, v28, vcc
	v_cndmask_b32_e32 v3, v2, v3, vcc
	v_mov_b32_e32 v2, s56
	v_mov_b32_e32 v4, s52
	v_cndmask_b32_e32 v2, v2, v4, vcc
	v_lshlrev_b64 v[0:1], 12, v[0:1]
	v_lshl_add_u64 v[0:1], v[2:3], 0, v[0:1]
	v_lshlrev_b32_e32 v2, 2, v20
	v_and_b32_e32 v22, 0xfc, v2
	v_mov_b32_e32 v17, 0
	v_lshlrev_b32_e32 v16, 2, v22
	v_lshl_add_u64 v[18:19], v[0:1], 0, v[16:17]
	global_load_dwordx4 v[12:15], v[18:19], off nt
	global_load_dwordx4 v[8:11], v[18:19], off offset:1024 nt
	global_load_dwordx4 v[4:7], v[18:19], off offset:2048 nt
	global_load_dwordx4 v[0:3], v[18:19], off offset:3072 nt
	v_mbcnt_lo_u32_b32 v18, -1, 0
	v_mbcnt_hi_u32_b32 v18, -1, v18
	v_and_b32_e32 v19, 64, v18
	v_add_u32_e32 v19, 64, v19
	v_xor_b32_e32 v21, 1, v18
	v_cmp_lt_i32_e32 vcc, v21, v19
	s_load_dword s6, s[90:91], 0x0
	s_add_u32 s4, s78, 0x1500000
	v_cndmask_b32_e32 v21, v18, v21, vcc
	v_lshlrev_b32_e32 v30, 2, v21
	v_xor_b32_e32 v21, 2, v18
	v_cmp_lt_i32_e32 vcc, v21, v19
	v_lshlrev_b64 v[38:39], 11, v[28:29]
	s_addc_u32 s5, s79, 0
	v_cndmask_b32_e32 v21, v18, v21, vcc
	v_lshlrev_b32_e32 v31, 2, v21
	v_xor_b32_e32 v21, 4, v18
	v_cmp_lt_i32_e32 vcc, v21, v19
	s_waitcnt lgkmcnt(0)
	s_lshl_b32 s6, s6, 3
	v_or_b32_e32 v24, 0x100, v22
	v_cndmask_b32_e32 v21, v18, v21, vcc
	v_lshlrev_b32_e32 v32, 2, v21
	v_xor_b32_e32 v21, 8, v18
	v_cmp_lt_i32_e32 vcc, v21, v19
	v_or_b32_e32 v26, 0x200, v22
	v_or_b32_e32 v36, 0x300, v22
	v_cndmask_b32_e32 v21, v18, v21, vcc
	v_lshlrev_b32_e32 v33, 2, v21
	v_xor_b32_e32 v21, 16, v18
	v_cmp_lt_i32_e32 vcc, v21, v19
	s_mov_b64 s[8:9], 0x4000000
	s_ashr_i32 s7, s6, 31
	v_cndmask_b32_e32 v21, v18, v21, vcc
	v_lshlrev_b32_e32 v34, 2, v21
	v_xor_b32_e32 v21, 32, v18
	v_cmp_lt_i32_e32 vcc, v21, v19
	s_mov_b64 s[10:11], 0
	s_mov_b64 s[12:13], 0x1000
	v_cndmask_b32_e32 v18, v18, v21, vcc
	v_lshlrev_b32_e32 v35, 2, v18
	v_lshl_add_u64 v[18:19], s[64:65], 0, v[16:17]
	v_and_b32_e32 v16, 63, v20
	v_lshl_or_b32 v38, v16, 3, v38
	v_lshl_add_u64 v[20:21], s[78:79], 0, v[38:39]
	v_lshl_add_u64 v[20:21], v[20:21], 0, s[8:9]
	s_lshl_b64 s[8:9], s[6:7], 11
	s_mov_b32 s7, 0x87ff
	v_lshlrev_b32_e32 v16, 2, v22
	v_mov_b32_e32 v29, 0x358637bd
	s_mov_b32 s15, 0x800000
	v_lshlrev_b32_e32 v22, 2, v24
	v_lshlrev_b32_e32 v24, 2, v26
	v_lshlrev_b32_e32 v26, 2, v36
	s_waitcnt vmcnt(0)
